# w_out and ff2 sample-row GEMM units split 4-way by row tile over all 256 WGs (each WG loads 1/4 of A), on top of pipelined sgemm loads
# speedup vs baseline: 1.0601x; 1.0514x over previous
.LBB0_1090:
	v_readlane_b32 s10, v254, 30
	v_readlane_b32 s11, v254, 31
	s_andn2_b64 vcc, exec, s[10:11]
	s_nop 0
	v_cndmask_b32_e64 v0, 0, 1, s[10:11]
	v_cmp_ne_u32_e64 s[92:93], 1, v0
	v_readlane_b32 s13, v254, 3
	s_nop 3
	s_cmpk_lt_i32 s13, 0x100
	s_cbranch_scc0 .LBB0_1099
	s_mov_b64 s[10:11], s[0:1]
	s_ashr_i32 s12, s4, 6
	s_load_dwordx4 s[36:39], s[10:11], 0xb8
	s_nop 0
	s_load_dwordx2 s[10:11], s[10:11], 0xd0
	s_cmp_eq_u32 s42, 0
	s_cselect_b64 s[28:29], -1, 0
	s_cmp_lg_u32 s42, 0
	s_cselect_b64 s[34:35], -1, 0
	s_lshl_b32 s4, s12, 4
	s_addk_i32 s4, 0x4000
	v_or_b32_e32 v0, s4, v245
	v_ashrrev_i32_e32 v1, 31, v0
	s_lshl_b32 s16, s12, 7
	s_waitcnt lgkmcnt(0)
	v_lshlrev_b64 v[2:3], 9, v[0:1]
	v_lshlrev_b64 v[0:1], 11, v[0:1]
	s_ashr_i32 s17, s16, 31
	v_lshl_add_u64 v[2:3], s[10:11], 0, v[2:3]
	v_lshl_add_u64 v[0:1], s[10:11], 0, v[0:1]
	s_mov_b64 s[10:11], 0x2a00000
	v_bfe_u32 v7, v244, 4, 2
	v_lshl_add_u64 v[42:43], v[0:1], 0, s[10:11]
	s_lshl_b32 s4, s12, 13
	s_lshl_b32 s12, s12, 10
	s_mov_b64 s[10:11], 0xe80e000
	s_lshl_b64 s[42:43], s[16:17], 1
	v_lshlrev_b32_e32 v174, 7, v7
	v_lshl_add_u64 v[44:45], v[2:3], 0, s[10:11]
	s_add_u32 s10, s40, s44
	v_lshl_add_u64 v[4:5], v[2:3], 0, v[174:175]
	v_and_b32_e32 v174, 48, v244
	s_addc_u32 s11, s41, s45
	v_and_b32_e32 v6, 63, v244
	s_mov_b64 s[20:21], 0xe81e000
	v_lshl_add_u64 v[46:47], s[10:11], 0, v[174:175]
	v_readlane_b32 s10, v255, 47
	v_lshl_or_b32 v174, v245, 11, v174
	v_lshl_add_u32 v55, v6, 4, 0
	v_lshl_add_u64 v[40:41], v[4:5], 0, s[20:21]
	v_lshlrev_b32_e32 v64, 2, v7
	v_cmp_gt_u32_e64 s[30:31], 16, v6
	v_add_u32_e32 v48, s10, v245
	v_lshl_add_u64 v[50:51], s[40:41], 0, v[174:175]
	v_readlane_b32 s13, v254, 3
	s_branch .LBB0_1093
.LBB0_1092:
	s_or_b64 exec, exec, s[10:11]
	s_add_i32 s13, s13, s3
	s_cmpk_lt_i32 s13, 0x100
	v_add_u32_e32 v48, s87, v48
	s_waitcnt lgkmcnt(0)
	s_barrier
	s_cbranch_scc0 .LBB0_1099
.LBB0_1093:
	s_lshr_b32 s100, s13, 2
	s_and_b32 s101, s13, 3
	v_lshl_add_u32 v48, s100, 4, v245
	v_mov_b32_e32 v8, 0
	v_mov_b32_e32 v54, 1.0
	s_andn2_b64 vcc, exec, s[34:35]
	v_mov_b32_e32 v56, 0
	s_cbranch_vccnz .LBB0_1095
	global_load_dwordx4 v[0:3], v[40:41], off
	global_load_dwordx4 v[4:7], v[40:41], off offset:16
	global_load_dwordx4 v[10:13], v[40:41], off offset:32
	global_load_dwordx4 v[14:17], v[40:41], off offset:48
	global_load_dwordx4 v[18:21], v[40:41], off offset:64
	global_load_dwordx4 v[22:25], v[40:41], off offset:80
	global_load_dwordx4 v[26:29], v[40:41], off offset:96
	global_load_dwordx4 v[30:33], v[40:41], off offset:112
	v_and_b32_e32 v34, 64, v237
	v_xor_b32_e32 v9, 16, v237
	v_add_u32_e32 v34, 64, v34
	v_cmp_lt_i32_e32 vcc, v9, v34
	s_waitcnt vmcnt(7)
	v_pk_add_f32 v[0:1], v[0:1], v[2:3]
	s_waitcnt vmcnt(6)
	v_pk_add_f32 v[2:3], v[4:5], v[6:7]
	v_pk_add_f32 v[0:1], v[0:1], 0 op_sel_hi:[1,0]
	s_waitcnt vmcnt(5)
	v_pk_add_f32 v[4:5], v[10:11], v[12:13]
	v_pk_add_f32 v[0:1], v[0:1], v[2:3]
	s_waitcnt vmcnt(4)
	v_pk_add_f32 v[6:7], v[14:15], v[16:17]
	v_pk_add_f32 v[0:1], v[0:1], v[4:5]
	s_waitcnt vmcnt(3)
	v_pk_add_f32 v[10:11], v[18:19], v[20:21]
	v_pk_add_f32 v[0:1], v[0:1], v[6:7]
	s_waitcnt vmcnt(2)
	v_pk_add_f32 v[12:13], v[22:23], v[24:25]
	v_pk_add_f32 v[0:1], v[0:1], v[10:11]
	s_waitcnt vmcnt(1)
	v_pk_add_f32 v[14:15], v[26:27], v[28:29]
	v_pk_add_f32 v[0:1], v[0:1], v[12:13]
	v_cndmask_b32_e32 v9, v237, v9, vcc
	s_waitcnt vmcnt(0)
	v_pk_add_f32 v[16:17], v[30:31], v[32:33]
	v_pk_add_f32 v[0:1], v[0:1], v[14:15]
	v_lshlrev_b32_e32 v9, 2, v9
	v_pk_add_f32 v[0:1], v[0:1], v[16:17]
	ds_bpermute_b32 v2, v9, v0
	ds_bpermute_b32 v3, v9, v1
	v_xor_b32_e32 v4, 32, v237
	v_cmp_lt_i32_e32 vcc, v4, v34
	s_waitcnt lgkmcnt(0)
	v_pk_add_f32 v[0:1], v[0:1], v[2:3]
	v_cndmask_b32_e32 v4, v237, v4, vcc
	v_lshlrev_b32_e32 v4, 2, v4
	ds_bpermute_b32 v2, v4, v0
	ds_bpermute_b32 v3, v4, v1
	s_waitcnt lgkmcnt(0)
	v_pk_add_f32 v[0:1], v[0:1], v[2:3]
	s_nop 0
	v_pk_mul_f32 v[56:57], v[0:1], s[6:7] op_sel_hi:[1,0]
	s_nop 0
	v_fma_f32 v0, -v56, v56, v57
	v_max_f32_e32 v0, 0, v0
	v_add_f32_e32 v0, 0x3727c5ac, v0
	v_mul_f32_e32 v1, 0x4b800000, v0
	v_cmp_gt_f32_e32 vcc, s14, v0
	s_nop 1
	v_cndmask_b32_e32 v0, v0, v1, vcc
	v_rsq_f32_e32 v0, v0
	s_nop 0
	v_mul_f32_e32 v1, 0x45800000, v0
	v_cndmask_b32_e32 v54, v0, v1, vcc
.LBB0_1095:
	v_lshl_or_b32 v10, s100, 4, v64
	v_ashrrev_i32_e32 v11, 31, v10
	v_lshlrev_b64 v[4:5], 2, v[10:11]
	v_lshl_add_u64 v[0:1], s[36:37], 0, v[4:5]
	v_lshl_add_u64 v[4:5], s[38:39], 0, v[4:5]
	v_lshl_add_u64 v[52:53], v[10:11], 1, v[42:43]
	global_load_dwordx4 v[0:3], v[0:1], off
	v_ashrrev_i32_e32 v49, 31, v48
	global_load_dwordx4 v[4:7], v[4:5], off
	v_lshlrev_b64 v[10:11], 11, v[48:49]
	global_load_dwordx2 v[58:59], v[52:53], off
	v_lshl_add_u64 v[60:61], v[46:47], 0, v[10:11]
	s_movk_i32 s10, 0xffe0
	v_mov_b64_e32 v[62:63], v[50:51]
	v_mov_b32_e32 v9, v8
	v_mov_b32_e32 v10, v8
	v_mov_b32_e32 v11, v8
	v_mov_b32_e32 v36, v8
	v_mov_b32_e32 v37, v8
	v_mov_b32_e32 v38, v8
	v_mov_b32_e32 v39, v8
	v_mov_b32_e32 v32, v8
	v_mov_b32_e32 v33, v8
	v_mov_b32_e32 v34, v8
	v_mov_b32_e32 v35, v8
	v_mov_b32_e32 v28, v8
	v_mov_b32_e32 v29, v8
	v_mov_b32_e32 v30, v8
	v_mov_b32_e32 v31, v8
	v_mov_b32_e32 v24, v8
	v_mov_b32_e32 v25, v8
	v_mov_b32_e32 v26, v8
	v_mov_b32_e32 v27, v8
	v_mov_b32_e32 v20, v8
	v_mov_b32_e32 v21, v8
	v_mov_b32_e32 v22, v8
	v_mov_b32_e32 v23, v8
	v_mov_b32_e32 v16, v8
	v_mov_b32_e32 v17, v8
	v_mov_b32_e32 v18, v8
	v_mov_b32_e32 v19, v8
	v_mov_b32_e32 v12, v8
	v_mov_b32_e32 v13, v8
	v_mov_b32_e32 v14, v8
	v_mov_b32_e32 v15, v8
.LBB0_1096:
	v_lshl_add_u64 v[66:67], v[60:61], 0, s[42:43]
	s_mov_b32 s11, 0x600000
	v_add_co_u32_e32 v74, vcc, s11, v66
	v_lshl_add_u64 v[76:77], v[62:63], 0, s[42:43]
	s_nop 1
	v_addc_co_u32_e32 v75, vcc, 0, v67, vcc
	s_lshl_b32 s10, s101, 16
	s_mov_b32 s11, 0
	v_lshl_add_u64 v[76:77], v[76:77], 0, s[10:11]
	v_add_co_u32_e32 v78, vcc, s52, v76
	s_mov_b32 s11, 0x6a48000
	s_nop 1
	v_addc_co_u32_e32 v79, vcc, 0, v77, vcc
	v_add_co_u32_e32 v80, vcc, s11, v76
	s_nop 1
	v_addc_co_u32_e32 v81, vcc, 0, v77, vcc
	global_load_dwordx4 v[118:121], v[74:75], off
	global_load_dwordx4 v[122:125], v[78:79], off
	global_load_dwordx4 v[126:129], v[80:81], off
	global_load_dwordx4 v[130:133], v[74:75], off offset:64
	global_load_dwordx4 v[134:137], v[78:79], off offset:64
	global_load_dwordx4 v[138:141], v[80:81], off offset:64
	global_load_dwordx4 v[142:145], v[74:75], off offset:128
	global_load_dwordx4 v[146:149], v[78:79], off offset:128
	global_load_dwordx4 v[150:153], v[80:81], off offset:128
	global_load_dwordx4 v[154:157], v[74:75], off offset:192
	global_load_dwordx4 v[158:161], v[78:79], off offset:192
	global_load_dwordx4 v[162:165], v[80:81], off offset:192
	s_waitcnt vmcnt(9)
	v_mfma_f32_16x16x32_bf16 v[36:39], v[118:121], v[122:125], v[36:39]
	v_mfma_f32_16x16x32_bf16 v[32:35], v[118:121], v[126:129], v[32:35]
	s_waitcnt vmcnt(6)
	v_mfma_f32_16x16x32_bf16 v[36:39], v[130:133], v[134:137], v[36:39]
	v_mfma_f32_16x16x32_bf16 v[32:35], v[130:133], v[138:141], v[32:35]
	s_waitcnt vmcnt(3)
	v_mfma_f32_16x16x32_bf16 v[36:39], v[142:145], v[146:149], v[36:39]
	v_mfma_f32_16x16x32_bf16 v[32:35], v[142:145], v[150:153], v[32:35]
	s_waitcnt vmcnt(0)
	v_mfma_f32_16x16x32_bf16 v[36:39], v[154:157], v[158:161], v[36:39]
	v_mfma_f32_16x16x32_bf16 v[32:35], v[154:157], v[162:165], v[32:35]
	s_nop 4
	v_add_u32_e32 v49, s4, v55
	v_lshl_add_u32 v49, s101, 11, v49
	ds_write_b128 v49, v[36:39]
	ds_write_b128 v49, v[32:35] offset:1024
	v_add_u32_e32 v24, s12, v55
	s_waitcnt lgkmcnt(0)
	s_barrier
	s_lshr_b32 s10, s12, 11
	s_cmp_lg_u32 s10, s101
	s_cbranch_scc1 .LBB0_1092
	ds_read_b128 v[8:11], v24
	ds_read_b128 v[12:15], v24 offset:8192
	ds_read_b128 v[16:19], v24 offset:16384
	s_waitcnt lgkmcnt(2)
	v_pk_add_f32 v[10:11], v[10:11], 0 op_sel_hi:[1,0]
	v_pk_add_f32 v[20:21], v[8:9], 0 op_sel_hi:[1,0]
	s_waitcnt lgkmcnt(1)
	v_pk_add_f32 v[14:15], v[10:11], v[14:15]
	ds_read_b128 v[8:11], v24 offset:24576
	v_pk_add_f32 v[20:21], v[20:21], v[12:13]
	s_waitcnt lgkmcnt(1)
	v_pk_add_f32 v[18:19], v[14:15], v[18:19]
	ds_read_b128 v[12:15], v24 offset:32768
	v_pk_add_f32 v[16:17], v[20:21], v[16:17]
	s_waitcnt lgkmcnt(1)
	v_pk_add_f32 v[18:19], v[18:19], v[10:11]
	v_pk_add_f32 v[20:21], v[16:17], v[8:9]
	ds_read_b128 v[8:11], v24 offset:40960
	s_waitcnt lgkmcnt(1)
	v_pk_add_f32 v[22:23], v[18:19], v[14:15]
	ds_read_b128 v[14:17], v24 offset:49152
	v_pk_add_f32 v[12:13], v[20:21], v[12:13]
	ds_read_b128 v[18:21], v24 offset:57344
	s_waitcnt lgkmcnt(2)
	v_pk_add_f32 v[8:9], v[12:13], v[8:9]
	v_pk_add_f32 v[10:11], v[22:23], v[10:11]
	s_waitcnt lgkmcnt(1)
	v_pk_add_f32 v[8:9], v[8:9], v[14:15]
	v_pk_add_f32 v[10:11], v[10:11], v[16:17]
	s_waitcnt lgkmcnt(0)
	v_pk_add_f32 v[8:9], v[8:9], v[18:19]
	v_lshlrev_b32_e32 v18, 16, v59
	v_and_b32_e32 v19, 0xffff0000, v59
	v_lshlrev_b32_e32 v16, 16, v58
	v_and_b32_e32 v17, 0xffff0000, v58
	v_sub_f32_e32 v13, v19, v56
	v_sub_f32_e32 v12, v18, v56
	v_sub_f32_e32 v15, v17, v56
	v_sub_f32_e32 v14, v16, v56
	v_pk_mul_f32 v[12:13], v[54:55], v[12:13] op_sel_hi:[0,1]
	v_pk_mul_f32 v[14:15], v[54:55], v[14:15] op_sel_hi:[0,1]
	v_pk_fma_f32 v[2:3], v[2:3], v[12:13], v[6:7]
	v_pk_add_f32 v[10:11], v[10:11], v[20:21]
	v_pk_fma_f32 v[0:1], v[0:1], v[14:15], v[4:5]
	v_cndmask_b32_e64 v3, v3, v19, s[28:29]
	v_cndmask_b32_e64 v2, v2, v18, s[28:29]
	v_cndmask_b32_e64 v1, v1, v17, s[28:29]
	v_cndmask_b32_e64 v0, v0, v16, s[28:29]
	v_pk_fma_f32 v[4:5], v[2:3], s[70:71], v[10:11] op_sel_hi:[1,0,1]
	v_and_b32_e32 v2, 64, v237
	v_pk_fma_f32 v[6:7], v[0:1], s[70:71], v[8:9] op_sel_hi:[1,0,1]
	v_xor_b32_e32 v0, 16, v237
	v_add_u32_e32 v12, 64, v2
	v_cmp_lt_i32_e32 vcc, v0, v12
	v_mul_f32_e32 v1, v6, v6
	v_mul_f32_e32 v3, v7, v7
	v_cndmask_b32_e32 v0, v237, v0, vcc
	v_mul_f32_e32 v9, v4, v4
	v_mul_f32_e32 v11, v5, v5
	v_lshlrev_b32_e32 v13, 2, v0
	v_mov_b32_e32 v0, v6
	v_mov_b32_e32 v2, v7
	v_mov_b32_e32 v8, v4
	v_mov_b32_e32 v10, v5
	v_pk_add_f32 v[0:1], v[0:1], v[2:3]
	v_pk_add_f32 v[2:3], v[8:9], v[10:11]
	v_xor_b32_e32 v8, 32, v237
	v_pk_add_f32 v[0:1], v[0:1], v[2:3]
	ds_bpermute_b32 v2, v13, v0
	ds_bpermute_b32 v3, v13, v1
	v_cmp_lt_i32_e32 vcc, v8, v12
	v_cvt_pk_bf16_f32 v6, v6, v7
	v_cvt_pk_bf16_f32 v7, v4, v5
	global_store_dwordx2 v[52:53], v[6:7], off
	s_waitcnt lgkmcnt(0)
	v_pk_add_f32 v[0:1], v[0:1], v[2:3]
	v_cndmask_b32_e32 v8, v237, v8, vcc
	v_lshlrev_b32_e32 v8, 2, v8
	ds_bpermute_b32 v2, v8, v0
	ds_bpermute_b32 v3, v8, v1
	s_and_saveexec_b64 s[10:11], s[30:31]
	s_cbranch_execz .LBB0_1092
	s_lshl_b32 s16, s100, 1
	s_ashr_i32 s17, s16, 31
	v_lshl_add_u64 v[4:5], s[16:17], 2, v[44:45]
	s_waitcnt lgkmcnt(0)
	v_pk_add_f32 v[0:1], v[0:1], v[2:3]
	global_store_dwordx2 v[4:5], v[0:1], off
	s_branch .LBB0_1092

.LBB0_1371:
	s_and_b64 vcc, exec, s[92:93]
	v_readlane_b32 s13, v254, 3
	s_nop 3
	s_cmpk_lt_i32 s13, 0x100
	s_cbranch_scc0 .LBB0_1378
	s_mov_b64 s[10:11], s[0:1]
	s_load_dwordx4 s[20:23], s[10:11], 0x98
	s_nop 0
	s_load_dwordx2 s[10:11], s[10:11], 0xd0
	s_lshl_b32 s12, s74, 10
	s_ashr_i32 s13, s12, 31
	s_ashr_i32 s34, s4, 6
	s_lshl_b64 s[12:13], s[12:13], 2
	s_waitcnt lgkmcnt(0)
	s_add_u32 s24, s20, s12
	s_addc_u32 s25, s21, s13
	s_add_u32 s26, s22, s12
	s_addc_u32 s27, s23, s13
	s_lshl_b32 s4, s34, 4
	s_addk_i32 s4, 0x4000
	v_or_b32_e32 v0, s4, v220
	v_ashrrev_i32_e32 v1, 31, v0
	v_bfe_u32 v7, v219, 4, 2
	v_lshlrev_b64 v[2:3], 9, v[0:1]
	s_lshl_b32 s16, s34, 9
	v_lshlrev_b32_e32 v174, 7, v7
	v_lshl_add_u64 v[2:3], s[10:11], 0, v[2:3]
	v_lshlrev_b64 v[0:1], 11, v[0:1]
	s_ashr_i32 s17, s16, 31
	v_lshl_add_u64 v[4:5], v[2:3], 0, v[174:175]
	s_mov_b64 s[12:13], 0xe80e000
	v_lshl_add_u64 v[0:1], s[10:11], 0, v[0:1]
	s_mov_b64 s[10:11], 0x2a00000
	v_lshl_add_u64 v[40:41], v[4:5], 0, s[12:13]
	v_lshl_add_u64 v[42:43], v[0:1], 0, s[10:11]
	s_lshl_b32 s4, s34, 13
	s_lshl_b32 s12, s34, 10
	s_mov_b64 s[10:11], 0xe81e000
	s_lshl_b64 s[34:35], s[16:17], 1
	v_lshl_add_u64 v[44:45], v[2:3], 0, s[10:11]
	v_cmp_lt_i32_e64 s[22:23], v218, v176
	s_add_u32 s10, s28, s30
	v_and_b32_e32 v174, 48, v219
	v_cndmask_b32_e64 v0, v237, v218, s[22:23]
	v_cmp_lt_i32_e64 s[22:23], v178, v176
	s_addc_u32 s11, s29, s31
	v_and_b32_e32 v6, 63, v219
	v_lshlrev_b32_e32 v66, 2, v0
	v_cndmask_b32_e64 v0, v237, v178, s[22:23]
	v_lshl_add_u64 v[46:47], s[10:11], 0, v[174:175]
	v_readlane_b32 s10, v255, 47
	v_lshl_or_b32 v174, v220, 13, v174
	v_lshl_add_u32 v64, v6, 4, 0
	v_lshlrev_b32_e32 v65, 2, v7
	v_cmp_gt_u32_e32 vcc, 16, v6
	v_lshlrev_b32_e32 v67, 2, v0
	v_add_u32_e32 v48, s10, v220
	v_lshl_add_u64 v[50:51], s[28:29], 0, v[174:175]
	v_readlane_b32 s13, v254, 3
	s_branch .LBB0_1374

.LBB0_1374:
	s_lshr_b32 s100, s13, 2
	s_and_b32 s101, s13, 3
	v_lshl_add_u32 v48, s100, 4, v220
	v_ashrrev_i32_e32 v49, 31, v48
	v_lshlrev_b64 v[0:1], 13, v[48:49]
	v_lshl_add_u64 v[52:53], v[46:47], 0, v[0:1]
	global_load_dwordx4 v[0:3], v[40:41], off offset:48
	global_load_dwordx4 v[4:7], v[40:41], off offset:32
	global_load_dwordx4 v[8:11], v[40:41], off offset:16
	global_load_dwordx4 v[12:15], v[40:41], off
	global_load_dwordx4 v[16:19], v[40:41], off offset:112
	global_load_dwordx4 v[20:23], v[40:41], off offset:96
	global_load_dwordx4 v[24:27], v[40:41], off offset:80
	global_load_dwordx4 v[28:31], v[40:41], off offset:64
	s_movk_i32 s10, 0xffe0
	v_mov_b64_e32 v[62:63], v[50:51]
	s_waitcnt vmcnt(7)
	v_pk_add_f32 v[0:1], v[0:1], v[2:3]
	s_waitcnt vmcnt(6)
	v_pk_add_f32 v[4:5], v[4:5], v[6:7]
	s_waitcnt vmcnt(5)
	v_pk_add_f32 v[8:9], v[8:9], v[10:11]
	s_waitcnt vmcnt(4)
	v_pk_add_f32 v[12:13], v[12:13], v[14:15]
	s_waitcnt vmcnt(0)
	v_pk_add_f32 v[2:3], v[28:29], v[30:31]
	v_pk_add_f32 v[12:13], v[12:13], 0 op_sel_hi:[1,0]
	s_nop 0
	v_pk_add_f32 v[8:9], v[12:13], v[8:9]
	s_nop 0
	v_pk_add_f32 v[4:5], v[8:9], v[4:5]
	v_lshl_or_b32 v8, s100, 4, v65
	v_pk_add_f32 v[0:1], v[4:5], v[0:1]
	v_ashrrev_i32_e32 v9, 31, v8
	v_pk_add_f32 v[0:1], v[0:1], v[2:3]
	v_pk_add_f32 v[2:3], v[24:25], v[26:27]
	v_lshlrev_b64 v[4:5], 2, v[8:9]
	v_pk_add_f32 v[0:1], v[0:1], v[2:3]
	v_pk_add_f32 v[2:3], v[20:21], v[22:23]
	v_lshl_add_u64 v[58:59], v[8:9], 1, v[42:43]
	v_pk_add_f32 v[0:1], v[0:1], v[2:3]
	v_pk_add_f32 v[2:3], v[16:17], v[18:19]
	global_load_dwordx2 v[60:61], v[58:59], off
	v_pk_add_f32 v[0:1], v[0:1], v[2:3]
	ds_bpermute_b32 v2, v66, v0
	ds_bpermute_b32 v3, v66, v1
	v_mov_b32_e32 v8, 0
	v_mov_b32_e32 v9, v8
	v_mov_b32_e32 v10, v8
	v_mov_b32_e32 v11, v8
	s_waitcnt lgkmcnt(0)
	v_pk_add_f32 v[54:55], v[0:1], v[2:3]
	v_lshl_add_u64 v[0:1], s[24:25], 0, v[4:5]
	v_lshl_add_u64 v[4:5], s[26:27], 0, v[4:5]
	global_load_dwordx4 v[0:3], v[0:1], off
	ds_bpermute_b32 v56, v67, v54
	global_load_dwordx4 v[4:7], v[4:5], off
	ds_bpermute_b32 v57, v67, v55
	v_mov_b32_e32 v28, v8
	v_mov_b32_e32 v29, v8
	v_mov_b32_e32 v30, v8
	v_mov_b32_e32 v31, v8
	v_mov_b32_e32 v24, v8
	v_mov_b32_e32 v25, v8
	v_mov_b32_e32 v26, v8
	v_mov_b32_e32 v27, v8
	v_mov_b32_e32 v20, v8
	v_mov_b32_e32 v21, v8
	v_mov_b32_e32 v22, v8
	v_mov_b32_e32 v23, v8
	v_mov_b32_e32 v16, v8
	v_mov_b32_e32 v17, v8
	v_mov_b32_e32 v18, v8
	v_mov_b32_e32 v19, v8
	v_mov_b32_e32 v12, v8
	v_mov_b32_e32 v13, v8
	v_mov_b32_e32 v14, v8
	v_mov_b32_e32 v15, v8
	v_mov_b32_e32 v32, v8
	v_mov_b32_e32 v33, v8
	v_mov_b32_e32 v34, v8
	v_mov_b32_e32 v35, v8
	v_mov_b32_e32 v36, v8
	v_mov_b32_e32 v37, v8
	v_mov_b32_e32 v38, v8
	v_mov_b32_e32 v39, v8
.LBB0_1375:
	v_lshl_add_u64 v[68:69], v[52:53], 0, s[34:35]
	s_mov_b32 s11, 0x1a00000
	v_add_co_u32_e64 v76, s[22:23], s11, v68
	v_lshl_add_u64 v[78:79], v[62:63], 0, s[34:35]
	s_nop 1
	v_addc_co_u32_e64 v77, s[22:23], 0, v69, s[22:23]
	s_lshl_b32 s10, s101, 18
	s_mov_b32 s11, 0
	v_lshl_add_u64 v[78:79], v[78:79], 0, s[10:11]
	s_mov_b32 s11, 0xea80000
	v_add_co_u32_e64 v80, s[22:23], s11, v78
	s_mov_b32 s11, 0xeaa0000
	s_nop 1
	v_addc_co_u32_e64 v81, s[22:23], 0, v79, s[22:23]
	v_add_co_u32_e64 v82, s[22:23], s11, v78
	s_nop 1
	v_addc_co_u32_e64 v83, s[22:23], 0, v79, s[22:23]
	global_load_dwordx4 v[118:121], v[76:77], off
	global_load_dwordx4 v[122:125], v[80:81], off
	global_load_dwordx4 v[126:129], v[82:83], off
	global_load_dwordx4 v[130:133], v[76:77], off offset:64
	global_load_dwordx4 v[134:137], v[80:81], off offset:64
	global_load_dwordx4 v[138:141], v[82:83], off offset:64
	global_load_dwordx4 v[142:145], v[76:77], off offset:128
	global_load_dwordx4 v[146:149], v[80:81], off offset:128
	global_load_dwordx4 v[150:153], v[82:83], off offset:128
	global_load_dwordx4 v[154:157], v[76:77], off offset:192
	global_load_dwordx4 v[158:161], v[80:81], off offset:192
	global_load_dwordx4 v[162:165], v[82:83], off offset:192
	global_load_dwordx4 v[166:169], v[76:77], off offset:256
	global_load_dwordx4 v[182:185], v[80:81], off offset:256
	global_load_dwordx4 v[186:189], v[82:83], off offset:256
	global_load_dwordx4 v[190:193], v[76:77], off offset:320
	global_load_dwordx4 v[194:197], v[80:81], off offset:320
	global_load_dwordx4 v[202:205], v[82:83], off offset:320
	global_load_dwordx4 v[206:209], v[76:77], off offset:384
	global_load_dwordx4 v[210:213], v[80:81], off offset:384
	global_load_dwordx4 v[214:217], v[82:83], off offset:384
	global_load_dwordx4 v[220:223], v[76:77], off offset:448
	global_load_dwordx4 v[224:227], v[80:81], off offset:448
	global_load_dwordx4 v[228:231], v[82:83], off offset:448
	s_waitcnt vmcnt(21)
	v_mfma_f32_16x16x32_bf16 v[28:31], v[118:121], v[122:125], v[28:31]
	v_mfma_f32_16x16x32_bf16 v[24:27], v[118:121], v[126:129], v[24:27]
	global_load_dwordx4 v[118:121], v[76:77], off offset:512
	global_load_dwordx4 v[122:125], v[80:81], off offset:512
	global_load_dwordx4 v[126:129], v[82:83], off offset:512
	s_waitcnt vmcnt(21)
	v_mfma_f32_16x16x32_bf16 v[28:31], v[130:133], v[134:137], v[28:31]
	v_mfma_f32_16x16x32_bf16 v[24:27], v[130:133], v[138:141], v[24:27]
	global_load_dwordx4 v[130:133], v[76:77], off offset:576
	global_load_dwordx4 v[134:137], v[80:81], off offset:576
	global_load_dwordx4 v[138:141], v[82:83], off offset:576
	s_waitcnt vmcnt(21)
	v_mfma_f32_16x16x32_bf16 v[28:31], v[142:145], v[146:149], v[28:31]
	v_mfma_f32_16x16x32_bf16 v[24:27], v[142:145], v[150:153], v[24:27]
	global_load_dwordx4 v[142:145], v[76:77], off offset:640
	global_load_dwordx4 v[146:149], v[80:81], off offset:640
	global_load_dwordx4 v[150:153], v[82:83], off offset:640
	s_waitcnt vmcnt(21)
	v_mfma_f32_16x16x32_bf16 v[28:31], v[154:157], v[158:161], v[28:31]
	v_mfma_f32_16x16x32_bf16 v[24:27], v[154:157], v[162:165], v[24:27]
	global_load_dwordx4 v[154:157], v[76:77], off offset:704
	global_load_dwordx4 v[158:161], v[80:81], off offset:704
	global_load_dwordx4 v[162:165], v[82:83], off offset:704
	s_waitcnt vmcnt(21)
	v_mfma_f32_16x16x32_bf16 v[28:31], v[166:169], v[182:185], v[28:31]
	v_mfma_f32_16x16x32_bf16 v[24:27], v[166:169], v[186:189], v[24:27]
	global_load_dwordx4 v[166:169], v[76:77], off offset:768
	global_load_dwordx4 v[182:185], v[80:81], off offset:768
	global_load_dwordx4 v[186:189], v[82:83], off offset:768
	s_waitcnt vmcnt(21)
	v_mfma_f32_16x16x32_bf16 v[28:31], v[190:193], v[194:197], v[28:31]
	v_mfma_f32_16x16x32_bf16 v[24:27], v[190:193], v[202:205], v[24:27]
	global_load_dwordx4 v[190:193], v[76:77], off offset:832
	global_load_dwordx4 v[194:197], v[80:81], off offset:832
	global_load_dwordx4 v[202:205], v[82:83], off offset:832
	s_waitcnt vmcnt(21)
	v_mfma_f32_16x16x32_bf16 v[28:31], v[206:209], v[210:213], v[28:31]
	v_mfma_f32_16x16x32_bf16 v[24:27], v[206:209], v[214:217], v[24:27]
	global_load_dwordx4 v[206:209], v[76:77], off offset:896
	global_load_dwordx4 v[210:213], v[80:81], off offset:896
	global_load_dwordx4 v[214:217], v[82:83], off offset:896
	s_waitcnt vmcnt(21)
	v_mfma_f32_16x16x32_bf16 v[28:31], v[220:223], v[224:227], v[28:31]
	v_mfma_f32_16x16x32_bf16 v[24:27], v[220:223], v[228:231], v[24:27]
	global_load_dwordx4 v[220:223], v[76:77], off offset:960
	global_load_dwordx4 v[224:227], v[80:81], off offset:960
	global_load_dwordx4 v[228:231], v[82:83], off offset:960
	s_waitcnt vmcnt(21)
	v_mfma_f32_16x16x32_bf16 v[28:31], v[118:121], v[122:125], v[28:31]
	v_mfma_f32_16x16x32_bf16 v[24:27], v[118:121], v[126:129], v[24:27]
	s_waitcnt vmcnt(18)
	v_mfma_f32_16x16x32_bf16 v[28:31], v[130:133], v[134:137], v[28:31]
	v_mfma_f32_16x16x32_bf16 v[24:27], v[130:133], v[138:141], v[24:27]
	s_waitcnt vmcnt(15)
	v_mfma_f32_16x16x32_bf16 v[28:31], v[142:145], v[146:149], v[28:31]
	v_mfma_f32_16x16x32_bf16 v[24:27], v[142:145], v[150:153], v[24:27]
	s_waitcnt vmcnt(12)
	v_mfma_f32_16x16x32_bf16 v[28:31], v[154:157], v[158:161], v[28:31]
	v_mfma_f32_16x16x32_bf16 v[24:27], v[154:157], v[162:165], v[24:27]
	s_waitcnt vmcnt(9)
	v_mfma_f32_16x16x32_bf16 v[28:31], v[166:169], v[182:185], v[28:31]
	v_mfma_f32_16x16x32_bf16 v[24:27], v[166:169], v[186:189], v[24:27]
	s_waitcnt vmcnt(6)
	v_mfma_f32_16x16x32_bf16 v[28:31], v[190:193], v[194:197], v[28:31]
	v_mfma_f32_16x16x32_bf16 v[24:27], v[190:193], v[202:205], v[24:27]
	s_waitcnt vmcnt(3)
	v_mfma_f32_16x16x32_bf16 v[28:31], v[206:209], v[210:213], v[28:31]
	v_mfma_f32_16x16x32_bf16 v[24:27], v[206:209], v[214:217], v[24:27]
	s_waitcnt vmcnt(0)
	v_mfma_f32_16x16x32_bf16 v[28:31], v[220:223], v[224:227], v[28:31]
	v_mfma_f32_16x16x32_bf16 v[24:27], v[220:223], v[228:231], v[24:27]
	s_nop 4
	s_waitcnt lgkmcnt(0)
	v_pk_add_f32 v[52:53], v[54:55], v[56:57]
	s_nop 0
	v_pk_mul_f32 v[52:53], v[52:53], s[6:7] op_sel_hi:[1,0]
	s_nop 0
	v_fma_f32 v49, -v52, v52, v53
	v_max_f32_e32 v49, 0, v49
	v_add_f32_e32 v49, 0x3727c5ac, v49
	v_mul_f32_e32 v53, 0x4b800000, v49
	v_cmp_gt_f32_e64 s[22:23], s14, v49
	s_nop 1
	v_cndmask_b32_e64 v49, v49, v53, s[22:23]
	v_rsq_f32_e32 v49, v49
	v_add_u32_e32 v53, s4, v64
	v_lshl_add_u32 v53, s101, 11, v53
	ds_write_b128 v53, v[28:31]
	ds_write_b128 v53, v[24:27] offset:1024
	v_add_u32_e32 v23, s12, v64
	s_waitcnt lgkmcnt(0)
	s_barrier
	s_lshr_b32 s10, s12, 11
	s_cmp_lg_u32 s10, s101
	s_cbranch_scc1 .LBB0_1373
	ds_read_b128 v[8:11], v23
	ds_read_b128 v[12:15], v23 offset:8192
	v_mul_f32_e32 v16, 0x45800000, v49
	v_cndmask_b32_e64 v22, v49, v16, s[22:23]
	ds_read_b128 v[16:19], v23 offset:16384
	s_waitcnt lgkmcnt(2)
	v_pk_add_f32 v[10:11], v[10:11], 0 op_sel_hi:[1,0]
	v_pk_add_f32 v[20:21], v[8:9], 0 op_sel_hi:[1,0]
	s_waitcnt lgkmcnt(1)
	v_pk_add_f32 v[14:15], v[10:11], v[14:15]
	ds_read_b128 v[8:11], v23 offset:24576
	v_pk_add_f32 v[20:21], v[20:21], v[12:13]
	s_waitcnt lgkmcnt(1)
	v_pk_add_f32 v[18:19], v[14:15], v[18:19]
	ds_read_b128 v[12:15], v23 offset:32768
	v_pk_add_f32 v[16:17], v[20:21], v[16:17]
	s_waitcnt lgkmcnt(1)
	v_pk_add_f32 v[18:19], v[18:19], v[10:11]
	v_pk_add_f32 v[20:21], v[16:17], v[8:9]
	ds_read_b128 v[8:11], v23 offset:40960
	s_waitcnt lgkmcnt(1)
	v_pk_add_f32 v[24:25], v[18:19], v[14:15]
	ds_read_b128 v[14:17], v23 offset:49152
	v_pk_add_f32 v[12:13], v[20:21], v[12:13]
	ds_read_b128 v[18:21], v23 offset:57344
	s_waitcnt lgkmcnt(2)
	v_pk_add_f32 v[8:9], v[12:13], v[8:9]
	v_lshlrev_b32_e32 v12, 16, v60
	s_waitcnt lgkmcnt(1)
	v_pk_add_f32 v[8:9], v[8:9], v[14:15]
	v_and_b32_e32 v13, 0xffff0000, v60
	v_lshlrev_b32_e32 v14, 16, v61
	v_and_b32_e32 v15, 0xffff0000, v61
	v_pk_add_f32 v[10:11], v[24:25], v[10:11]
	v_sub_f32_e32 v13, v13, v52
	v_sub_f32_e32 v12, v12, v52
	v_sub_f32_e32 v15, v15, v52
	v_sub_f32_e32 v14, v14, v52
	v_pk_add_f32 v[10:11], v[10:11], v[16:17]
	v_pk_mul_f32 v[14:15], v[14:15], v[22:23] op_sel_hi:[1,0]
	v_pk_mul_f32 v[12:13], v[12:13], v[22:23] op_sel_hi:[1,0]
	s_waitcnt lgkmcnt(0)
	v_pk_add_f32 v[10:11], v[10:11], v[20:21]
	v_pk_add_f32 v[8:9], v[8:9], v[18:19]
	v_pk_fma_f32 v[0:1], v[0:1], v[12:13], v[4:5]
	v_pk_fma_f32 v[2:3], v[2:3], v[14:15], v[6:7]
	v_pk_fma_f32 v[6:7], v[0:1], s[70:71], v[8:9] op_sel_hi:[1,0,1]
	v_pk_fma_f32 v[4:5], v[2:3], s[70:71], v[10:11] op_sel_hi:[1,0,1]
	v_mul_f32_e32 v1, v6, v6
	v_mul_f32_e32 v3, v7, v7
	v_mul_f32_e32 v9, v4, v4
	v_mul_f32_e32 v11, v5, v5
	v_mov_b32_e32 v0, v6
	v_mov_b32_e32 v2, v7
	v_mov_b32_e32 v8, v4
	v_mov_b32_e32 v10, v5
	v_pk_add_f32 v[0:1], v[0:1], v[2:3]
	v_pk_add_f32 v[2:3], v[8:9], v[10:11]
	v_cvt_pk_bf16_f32 v6, v6, v7
	v_cvt_pk_bf16_f32 v7, v4, v5
	global_store_dwordx2 v[58:59], v[6:7], off
	v_pk_add_f32 v[0:1], v[0:1], v[2:3]
	ds_bpermute_b32 v2, v66, v0
	ds_bpermute_b32 v3, v66, v1
	s_waitcnt lgkmcnt(0)
	v_pk_add_f32 v[0:1], v[0:1], v[2:3]
	ds_bpermute_b32 v2, v67, v0
	ds_bpermute_b32 v3, v67, v1
	s_and_saveexec_b64 s[10:11], vcc
	s_cbranch_execz .LBB0_1373
	s_lshl_b32 s16, s100, 1
	s_ashr_i32 s17, s16, 31
	v_lshl_add_u64 v[4:5], s[16:17], 2, v[44:45]
	s_waitcnt lgkmcnt(0)
	v_pk_add_f32 v[0:1], v[0:1], v[2:3]
	global_store_dwordx2 v[4:5], v[0:1], off
	s_branch .LBB0_1373

	.amdhsa_kernel _Z10hybrid_fwd6Params
		.amdhsa_group_segment_fixed_size 0
		.amdhsa_private_segment_fixed_size 0
		.amdhsa_kernarg_size 472
		.amdhsa_user_sgpr_count 2
		.amdhsa_user_sgpr_dispatch_ptr 0
		.amdhsa_user_sgpr_queue_ptr 0
		.amdhsa_user_sgpr_kernarg_segment_ptr 1
		.amdhsa_user_sgpr_dispatch_id 0
		.amdhsa_user_sgpr_kernarg_preload_length 0
		.amdhsa_user_sgpr_kernarg_preload_offset 0
		.amdhsa_user_sgpr_private_segment_size 0
		.amdhsa_uses_dynamic_stack 0
		.amdhsa_enable_private_segment 0
		.amdhsa_system_sgpr_workgroup_id_x 1
		.amdhsa_system_sgpr_workgroup_id_y 0
		.amdhsa_system_sgpr_workgroup_id_z 0
		.amdhsa_system_sgpr_workgroup_info 0
		.amdhsa_system_vgpr_workitem_id 2
		.amdhsa_next_free_vgpr 256
		.amdhsa_next_free_sgpr 102
		.amdhsa_accum_offset 256
		.amdhsa_reserve_vcc 1
		.amdhsa_float_round_mode_32 0
		.amdhsa_float_round_mode_16_64 0
		.amdhsa_float_denorm_mode_32 3
		.amdhsa_float_denorm_mode_16_64 3
		.amdhsa_dx10_clamp 1
		.amdhsa_ieee_mode 1
		.amdhsa_fp16_overflow 0
		.amdhsa_tg_split 0
		.amdhsa_exception_fp_ieee_invalid_op 0
		.amdhsa_exception_fp_denorm_src 0
		.amdhsa_exception_fp_ieee_div_zero 0
		.amdhsa_exception_fp_ieee_overflow 0
		.amdhsa_exception_fp_ieee_underflow 0
		.amdhsa_exception_fp_ieee_inexact 0
		.amdhsa_exception_int_div_zero 0
	.end_amdhsa_kernel

amdhsa.kernels:
  - .agpr_count:     0
    .args:
      - .offset:         0
        .size:           216
        .value_kind:     by_value
      - .offset:         216
        .size:           4
        .value_kind:     hidden_block_count_x
      - .offset:         220
        .size:           4
        .value_kind:     hidden_block_count_y
      - .offset:         224
        .size:           4
        .value_kind:     hidden_block_count_z
      - .offset:         228
        .size:           2
        .value_kind:     hidden_group_size_x
      - .offset:         230
        .size:           2
        .value_kind:     hidden_group_size_y
      - .offset:         232
        .size:           2
        .value_kind:     hidden_group_size_z
      - .offset:         234
        .size:           2
        .value_kind:     hidden_remainder_x
      - .offset:         236
        .size:           2
        .value_kind:     hidden_remainder_y
      - .offset:         238
        .size:           2
        .value_kind:     hidden_remainder_z
      - .offset:         256
        .size:           8
        .value_kind:     hidden_global_offset_x
      - .offset:         264
        .size:           8
        .value_kind:     hidden_global_offset_y
      - .offset:         272
        .size:           8
        .value_kind:     hidden_global_offset_z
      - .offset:         280
        .size:           2
        .value_kind:     hidden_grid_dims
      - .offset:         304
        .size:           8
        .value_kind:     hidden_multigrid_sync_arg
      - .offset:         336
        .size:           4
        .value_kind:     hidden_dynamic_lds_size
    .group_segment_fixed_size: 0
    .kernarg_segment_align: 8
    .kernarg_segment_size: 472
    .language:       OpenCL C
    .language_version:
      - 2
      - 0
    .max_flat_workgroup_size: 512
    .name:           _Z10hybrid_fwd6Params
    .private_segment_fixed_size: 0
    .sgpr_count:     108
    .sgpr_spill_count: 125
    .symbol:         _Z10hybrid_fwd6Params.kd
    .uniform_work_group_size: 1
    .uses_dynamic_stack: false
    .vgpr_count:     256
    .vgpr_spill_count: 0
    .wavefront_size: 64
